# v044 plus scalar/address setup of load segments 2-4 hoisted into the preceding MFMA block (FFN-up K-loop)
# baseline (speedup 1.0000x reference)
; #define PG8_STAGE(bufoff, gbase, voff) do { _Pragma("unroll") for (int _i = 0; _i < 2; ++_i) \
;         __builtin_amdgcn_global_load_lds((const unsigned*)((const char*)(gbase) + (voff)[_i]), (LAS unsigned*)(lds + (bufoff) + ldsw + _i * 8192), 16, 0, 0); } while (0)
; #define PG8_LDA(dst, b, h) do { _Pragma("unroll") for (int m = 0; m < 4; ++m) _Pragma("unroll") for (int k = 0; k < 2; ++k) dst[m][k] = *(const LAS bf16x8*)(lds + PG8_SA(b, h) + aoff + m * 2048 + k * 1024); } while (0)
; #define PG8_LDB(dst, b, h) do { _Pragma("unroll") for (int n = 0; n < 2; ++n) _Pragma("unroll") for (int k = 0; k < 2; ++k) dst[n][k] = *(const LAS bf16x8*)(lds + PG8_SB(b, h) + boff + n * 2048 + k * 1024); } while (0)
; #define PG8_MMA(ai, bj, At, Bt) do { __builtin_amdgcn_s_setprio(1); _Pragma("unroll") for (int m = 0; m < 4; ++m) _Pragma("unroll") for (int n = 0; n < 2; ++n) _Pragma("unroll") for (int k = 0; k < 2; ++k) \
;         acc[ai][bj][m][n] = __builtin_amdgcn_mfma_f32_16x16x32_bf16(Bt[n][k], At[m][k], acc[ai][bj][m][n], 0, 0, 0); __builtin_amdgcn_s_setprio(0); } while (0)
; #define PG8_WAIT_V(n) asm volatile("s_waitcnt vmcnt(" #n ")" ::: "memory")
; #define PG8_WAIT_L(n) asm volatile("s_waitcnt lgkmcnt(" #n ")" ::: "memory")
; #define PG8_BAR __builtin_amdgcn_s_barrier()
; #define PG8_SCHED __builtin_amdgcn_sched_barrier(0)
; template <class Epi, bool ALIGN_EPI, bool SP2, bool ROWHALF = false>
; DI void gemm_phase(LAS unsigned char* lds, const Gemm g, const StaticOrder& S, const Epi& E) {
;     ...
;             if constexpr (SP2) {
;             PG8_LDB(B0, 0, 0); PG8_LDB(B1, 0, 1); PG8_SCHED; PG8_LDA(At, 0, 0); PG8_STAGE(PG8_SA(1, 1), a1 + hA1, voffA);
;             PG8_WAIT_V(8); PG8_WAIT_L(0); PG8_BAR; PG8_MMA(0, 0, At, B0); PG8_MMA(0, 1, At, B1); PG8_BAR; PG8_SCHED;
;             if constexpr (!ROWHALF) { PG8_LDA(At, 0, 1); } PG8_STAGE(PG8_SB(0, 0), b2, voffB); PG8_STAGE(PG8_SB(0, 1), b2 + hstepB, voffB); PG8_STAGE(PG8_SA(0, 0), a2 + hA0, voffA);
;             PG8_WAIT_V(8); PG8_WAIT_L(0); PG8_BAR; if constexpr (!ROWHALF) { PG8_MMA(1, 0, At, B0); PG8_MMA(1, 1, At, B1); } PG8_BAR; PG8_SCHED;
.Lk240_body:
	v_add_u32_e32 v156, s54, v145
	v_add_u32_e32 v160, s55, v145
	ds_read_b128 v[140:143], v156
	ds_read_b128 v[148:151], v156 offset:1024
	ds_read_b128 v[152:155], v156 offset:2048
	ds_read_b128 v[156:159], v156 offset:3072
	ds_read_b128 v[164:167], v160
	ds_read_b128 v[168:171], v160 offset:1024
	ds_read_b128 v[172:175], v160 offset:2048
	ds_read_b128 v[176:179], v160 offset:3072
	v_lshl_add_u64 v[160:161], s[74:75], 0, v[136:137]
	s_add_i32 m0, s9, 0xc000
	ds_read_b128 v[180:183], v147
	ds_read_b128 v[184:187], v147 offset:1024
	ds_read_b128 v[216:219], v147 offset:2048
	ds_read_b128 v[220:223], v147 offset:3072
	ds_read_b128 v[224:227], v147 offset:4096
	ds_read_b128 v[228:231], v147 offset:5120
	ds_read_b128 v[232:235], v147 offset:6144
	ds_read_b128 v[236:239], v147 offset:7168
	global_load_lds_dwordx4 v[160:161], off
	v_lshl_add_u64 v[160:161], s[74:75], 0, v[138:139]
	s_add_i32 m0, s9, 0xe000
	s_nop 0
	global_load_lds_dwordx4 v[160:161], off
	s_waitcnt vmcnt(8)
	s_waitcnt lgkmcnt(0)
	s_setprio 1
	v_mfma_f32_16x16x32_bf16 v[126:129], v[140:143], v[180:183], v[126:129]
	v_mfma_f32_16x16x32_bf16 v[118:121], v[152:155], v[180:183], v[118:121]
	v_mfma_f32_16x16x32_bf16 v[110:113], v[140:143], v[216:219], v[110:113]
	v_mfma_f32_16x16x32_bf16 v[102:105], v[152:155], v[216:219], v[102:105]
	s_barrier
	v_mfma_f32_16x16x32_bf16 v[92:95], v[140:143], v[224:227], v[92:95]
	v_mfma_f32_16x16x32_bf16 v[84:87], v[152:155], v[224:227], v[84:87]
	v_mfma_f32_16x16x32_bf16 v[76:79], v[140:143], v[232:235], v[76:79]
	v_mfma_f32_16x16x32_bf16 v[68:71], v[152:155], v[232:235], v[68:71]
	v_mfma_f32_16x16x32_bf16 v[126:129], v[148:151], v[184:187], v[126:129]
	v_mfma_f32_16x16x32_bf16 v[118:121], v[156:159], v[184:187], v[118:121]
	v_mfma_f32_16x16x32_bf16 v[110:113], v[148:151], v[220:223], v[110:113]
	v_mfma_f32_16x16x32_bf16 v[102:105], v[156:159], v[220:223], v[102:105]
	v_mfma_f32_16x16x32_bf16 v[92:95], v[148:151], v[228:231], v[92:95]
	v_mfma_f32_16x16x32_bf16 v[84:87], v[156:159], v[228:231], v[84:87]
	v_mfma_f32_16x16x32_bf16 v[76:79], v[148:151], v[236:239], v[76:79]
	v_mfma_f32_16x16x32_bf16 v[68:71], v[156:159], v[236:239], v[68:71]
	s_setprio 0
	s_setprio 1
	v_mfma_f32_16x16x32_bf16 v[122:125], v[164:167], v[180:183], v[122:125]
	v_mfma_f32_16x16x32_bf16 v[114:117], v[172:175], v[180:183], v[114:117]
	v_mfma_f32_16x16x32_bf16 v[106:109], v[164:167], v[216:219], v[106:109]
	v_mfma_f32_16x16x32_bf16 v[98:101], v[172:175], v[216:219], v[98:101]
	v_mfma_f32_16x16x32_bf16 v[88:91], v[164:167], v[224:227], v[88:91]
	v_mfma_f32_16x16x32_bf16 v[80:83], v[172:175], v[224:227], v[80:83]
	v_mfma_f32_16x16x32_bf16 v[72:75], v[164:167], v[232:235], v[72:75]
	v_mfma_f32_16x16x32_bf16 v[64:67], v[172:175], v[232:235], v[64:67]
	v_mfma_f32_16x16x32_bf16 v[122:125], v[168:171], v[184:187], v[122:125]
	s_add_i32 s36, s54, s8
	v_mfma_f32_16x16x32_bf16 v[114:117], v[176:179], v[184:187], v[114:117]
	v_lshl_add_u64 v[160:161], s[76:77], 0, v[96:97]
	v_mfma_f32_16x16x32_bf16 v[106:109], v[168:171], v[220:223], v[106:109]
	s_mov_b32 m0, s36
	v_mfma_f32_16x16x32_bf16 v[98:101], v[176:179], v[220:223], v[98:101]
	v_mfma_f32_16x16x32_bf16 v[88:91], v[168:171], v[228:231], v[88:91]
	v_mfma_f32_16x16x32_bf16 v[80:83], v[176:179], v[228:231], v[80:83]
	v_mfma_f32_16x16x32_bf16 v[72:75], v[168:171], v[236:239], v[72:75]
	v_mfma_f32_16x16x32_bf16 v[64:67], v[176:179], v[236:239], v[64:67]
	s_setprio 0
	s_barrier
	ds_read_b128 v[180:183], v147 offset:16384
	ds_read_b128 v[184:187], v147 offset:17408
	ds_read_b128 v[216:219], v147 offset:18432
	ds_read_b128 v[220:223], v147 offset:19456
	ds_read_b128 v[224:227], v147 offset:20480
	ds_read_b128 v[228:231], v147 offset:21504
	ds_read_b128 v[232:235], v147 offset:22528
	ds_read_b128 v[236:239], v147 offset:23552
	global_load_lds_dwordx4 v[160:161], off
	s_add_i32 m0, s36, 0x2000
	s_add_u32 s36, s76, 0x80000
	v_lshl_add_u64 v[240:241], s[76:77], 0, v[130:131]
	s_addc_u32 s37, s77, 0
	s_add_i32 s54, s55, s8
	global_load_lds_dwordx4 v[240:241], off
	v_lshl_add_u64 v[242:243], s[36:37], 0, v[96:97]
	s_mov_b32 m0, s54
	v_lshl_add_u64 v[244:245], s[78:79], 0, v[132:133]
	global_load_lds_dwordx4 v[242:243], off
	v_lshl_add_u64 v[242:243], s[36:37], 0, v[130:131]
	s_add_i32 m0, s54, 0x2000
	s_nop 0
	global_load_lds_dwordx4 v[242:243], off
	v_lshl_add_u64 v[242:243], s[78:79], 0, v[134:135]
	s_mov_b32 m0, s9
	s_nop 0
	global_load_lds_dwordx4 v[242:243], off
	s_mov_b32 m0, s10
	s_nop 0
	global_load_lds_dwordx4 v[244:245], off
	s_waitcnt vmcnt(8)
	s_waitcnt lgkmcnt(0)
	s_setprio 1
	v_mfma_f32_16x16x32_bf16 v[60:63], v[140:143], v[180:183], v[60:63]
	v_mfma_f32_16x16x32_bf16 v[52:55], v[152:155], v[180:183], v[52:55]
	v_mfma_f32_16x16x32_bf16 v[44:47], v[140:143], v[216:219], v[44:47]
	v_mfma_f32_16x16x32_bf16 v[36:39], v[152:155], v[216:219], v[36:39]
	s_barrier
; #define PG8_STAGE(bufoff, gbase, voff) do { _Pragma("unroll") for (int _i = 0; _i < 2; ++_i) \
;         __builtin_amdgcn_global_load_lds((const unsigned*)((const char*)(gbase) + (voff)[_i]), (LAS unsigned*)(lds + (bufoff) + ldsw + _i * 8192), 16, 0, 0); } while (0)
; #define PG8_LDA(dst, b, h) do { _Pragma("unroll") for (int m = 0; m < 4; ++m) _Pragma("unroll") for (int k = 0; k < 2; ++k) dst[m][k] = *(const LAS bf16x8*)(lds + PG8_SA(b, h) + aoff + m * 2048 + k * 1024); } while (0)
; #define PG8_LDB(dst, b, h) do { _Pragma("unroll") for (int n = 0; n < 2; ++n) _Pragma("unroll") for (int k = 0; k < 2; ++k) dst[n][k] = *(const LAS bf16x8*)(lds + PG8_SB(b, h) + boff + n * 2048 + k * 1024); } while (0)
; #define PG8_MMA(ai, bj, At, Bt) do { __builtin_amdgcn_s_setprio(1); _Pragma("unroll") for (int m = 0; m < 4; ++m) _Pragma("unroll") for (int n = 0; n < 2; ++n) _Pragma("unroll") for (int k = 0; k < 2; ++k) \
;         acc[ai][bj][m][n] = __builtin_amdgcn_mfma_f32_16x16x32_bf16(Bt[n][k], At[m][k], acc[ai][bj][m][n], 0, 0, 0); __builtin_amdgcn_s_setprio(0); } while (0)
; #define PG8_WAIT_V(n) asm volatile("s_waitcnt vmcnt(" #n ")" ::: "memory")
; #define PG8_WAIT_L(n) asm volatile("s_waitcnt lgkmcnt(" #n ")" ::: "memory")
; #define PG8_BAR __builtin_amdgcn_s_barrier()
; #define PG8_SCHED __builtin_amdgcn_sched_barrier(0)
; template <class Epi, bool ALIGN_EPI, bool SP2, bool ROWHALF = false>
; DI void gemm_phase(LAS unsigned char* lds, const Gemm g, const StaticOrder& S, const Epi& E) {
;     ...
;             PG8_WAIT_V(8); PG8_WAIT_L(0); PG8_BAR; if constexpr (!ROWHALF) { PG8_MMA(1, 0, At, B0); PG8_MMA(1, 1, At, B1); } PG8_BAR; PG8_SCHED;
;             PG8_LDB(B0, 1, 0); PG8_LDB(B1, 1, 1); PG8_SCHED; PG8_LDA(At, 1, 0); PG8_STAGE(PG8_SA(0, 1), a2 + hA1, voffA);
;             PG8_WAIT_V(8); PG8_WAIT_L(0); PG8_BAR; PG8_MMA(0, 0, At, B0); PG8_MMA(0, 1, At, B1); PG8_BAR; PG8_SCHED;
	v_mfma_f32_16x16x32_bf16 v[28:31], v[140:143], v[224:227], v[28:31]
	v_mfma_f32_16x16x32_bf16 v[20:23], v[152:155], v[224:227], v[20:23]
	v_mfma_f32_16x16x32_bf16 v[12:15], v[140:143], v[232:235], v[12:15]
	v_mfma_f32_16x16x32_bf16 v[4:7], v[152:155], v[232:235], v[4:7]
	v_mfma_f32_16x16x32_bf16 v[60:63], v[148:151], v[184:187], v[60:63]
	v_mfma_f32_16x16x32_bf16 v[52:55], v[156:159], v[184:187], v[52:55]
	v_mfma_f32_16x16x32_bf16 v[44:47], v[148:151], v[220:223], v[44:47]
	v_mfma_f32_16x16x32_bf16 v[36:39], v[156:159], v[220:223], v[36:39]
	v_mfma_f32_16x16x32_bf16 v[28:31], v[148:151], v[228:231], v[28:31]
	v_mfma_f32_16x16x32_bf16 v[20:23], v[156:159], v[228:231], v[20:23]
	v_mfma_f32_16x16x32_bf16 v[12:15], v[148:151], v[236:239], v[12:15]
	v_mfma_f32_16x16x32_bf16 v[4:7], v[156:159], v[236:239], v[4:7]
	s_setprio 0
	s_setprio 1
	v_mfma_f32_16x16x32_bf16 v[56:59], v[164:167], v[180:183], v[56:59]
	v_mfma_f32_16x16x32_bf16 v[48:51], v[172:175], v[180:183], v[48:51]
	v_mfma_f32_16x16x32_bf16 v[40:43], v[164:167], v[216:219], v[40:43]
	v_mfma_f32_16x16x32_bf16 v[32:35], v[172:175], v[216:219], v[32:35]
	v_mfma_f32_16x16x32_bf16 v[24:27], v[164:167], v[224:227], v[24:27]
	v_mfma_f32_16x16x32_bf16 v[16:19], v[172:175], v[224:227], v[16:19]
	v_mfma_f32_16x16x32_bf16 v[8:11], v[164:167], v[232:235], v[8:11]
	v_mfma_f32_16x16x32_bf16 v[0:3], v[172:175], v[232:235], v[0:3]
	v_mfma_f32_16x16x32_bf16 v[56:59], v[168:171], v[184:187], v[56:59]
	s_add_i32 s54, 0, 0x18000
	v_mfma_f32_16x16x32_bf16 v[48:51], v[176:179], v[184:187], v[48:51]
	s_add_i32 s55, 0, 0x1c000
	v_mfma_f32_16x16x32_bf16 v[40:43], v[168:171], v[220:223], v[40:43]
	s_add_u32 s36, s78, 0x80000
	s_addc_u32 s37, s79, 0
	v_mfma_f32_16x16x32_bf16 v[32:35], v[176:179], v[220:223], v[32:35]
	s_mov_b32 m0, s11
	v_mfma_f32_16x16x32_bf16 v[24:27], v[168:171], v[228:231], v[24:27]
	v_lshl_add_u64 v[246:247], s[36:37], 0, v[134:135]
	v_mfma_f32_16x16x32_bf16 v[16:19], v[176:179], v[228:231], v[16:19]
	v_mfma_f32_16x16x32_bf16 v[8:11], v[168:171], v[236:239], v[8:11]
	v_mfma_f32_16x16x32_bf16 v[0:3], v[176:179], v[236:239], v[0:3]
	s_setprio 0
	s_barrier
	v_add_u32_e32 v156, s54, v145
	v_add_u32_e32 v176, s55, v145
	ds_read_b128 v[140:143], v156
	ds_read_b128 v[148:151], v156 offset:1024
	ds_read_b128 v[152:155], v156 offset:2048
	ds_read_b128 v[156:159], v156 offset:3072
	ds_read_b128 v[164:167], v176
	ds_read_b128 v[168:171], v176 offset:1024
	ds_read_b128 v[172:175], v176 offset:2048
	ds_read_b128 v[176:179], v176 offset:3072
	ds_read_b128 v[180:183], v147 offset:32768
	ds_read_b128 v[184:187], v147 offset:33792
	ds_read_b128 v[216:219], v147 offset:34816
	ds_read_b128 v[220:223], v147 offset:35840
	ds_read_b128 v[224:227], v147 offset:36864
	ds_read_b128 v[228:231], v147 offset:37888
	ds_read_b128 v[232:235], v147 offset:38912
	ds_read_b128 v[236:239], v147 offset:39936
	global_load_lds_dwordx4 v[246:247], off
	v_lshl_add_u64 v[246:247], s[36:37], 0, v[132:133]
	s_mov_b32 m0, s12
	s_nop 0
	global_load_lds_dwordx4 v[246:247], off
	s_waitcnt vmcnt(8)
	s_waitcnt lgkmcnt(0)
	s_setprio 1
	v_mfma_f32_16x16x32_bf16 v[126:129], v[140:143], v[180:183], v[126:129]
	v_mfma_f32_16x16x32_bf16 v[118:121], v[152:155], v[180:183], v[118:121]
	v_mfma_f32_16x16x32_bf16 v[110:113], v[140:143], v[216:219], v[110:113]
	v_mfma_f32_16x16x32_bf16 v[102:105], v[152:155], v[216:219], v[102:105]
	s_barrier
	v_mfma_f32_16x16x32_bf16 v[92:95], v[140:143], v[224:227], v[92:95]
	v_mfma_f32_16x16x32_bf16 v[84:87], v[152:155], v[224:227], v[84:87]
	v_mfma_f32_16x16x32_bf16 v[76:79], v[140:143], v[232:235], v[76:79]
	v_mfma_f32_16x16x32_bf16 v[68:71], v[152:155], v[232:235], v[68:71]
	v_mfma_f32_16x16x32_bf16 v[126:129], v[148:151], v[184:187], v[126:129]
	v_mfma_f32_16x16x32_bf16 v[118:121], v[156:159], v[184:187], v[118:121]
	v_mfma_f32_16x16x32_bf16 v[110:113], v[148:151], v[220:223], v[110:113]
	v_mfma_f32_16x16x32_bf16 v[102:105], v[156:159], v[220:223], v[102:105]
	v_mfma_f32_16x16x32_bf16 v[92:95], v[148:151], v[228:231], v[92:95]
	v_mfma_f32_16x16x32_bf16 v[84:87], v[156:159], v[228:231], v[84:87]
	v_mfma_f32_16x16x32_bf16 v[76:79], v[148:151], v[236:239], v[76:79]
	v_mfma_f32_16x16x32_bf16 v[68:71], v[156:159], v[236:239], v[68:71]
	s_setprio 0
	s_setprio 1
	v_mfma_f32_16x16x32_bf16 v[122:125], v[164:167], v[180:183], v[122:125]
	v_mfma_f32_16x16x32_bf16 v[114:117], v[172:175], v[180:183], v[114:117]
	v_mfma_f32_16x16x32_bf16 v[106:109], v[164:167], v[216:219], v[106:109]
	v_mfma_f32_16x16x32_bf16 v[98:101], v[172:175], v[216:219], v[98:101]
	v_mfma_f32_16x16x32_bf16 v[88:91], v[164:167], v[224:227], v[88:91]
	v_mfma_f32_16x16x32_bf16 v[80:83], v[172:175], v[224:227], v[80:83]
	v_mfma_f32_16x16x32_bf16 v[72:75], v[164:167], v[232:235], v[72:75]
	v_mfma_f32_16x16x32_bf16 v[64:67], v[172:175], v[232:235], v[64:67]
	v_mfma_f32_16x16x32_bf16 v[122:125], v[168:171], v[184:187], v[122:125]
	s_add_i32 s36, s54, s8
	v_mfma_f32_16x16x32_bf16 v[114:117], v[176:179], v[184:187], v[114:117]
	v_lshl_add_u64 v[160:161], v[160:161], 0, s[38:39]
	v_mfma_f32_16x16x32_bf16 v[106:109], v[168:171], v[220:223], v[106:109]
	s_mov_b32 m0, s36
	v_mfma_f32_16x16x32_bf16 v[98:101], v[176:179], v[220:223], v[98:101]
	v_mfma_f32_16x16x32_bf16 v[88:91], v[168:171], v[228:231], v[88:91]
	v_mfma_f32_16x16x32_bf16 v[80:83], v[176:179], v[228:231], v[80:83]
	v_mfma_f32_16x16x32_bf16 v[72:75], v[168:171], v[236:239], v[72:75]
	v_mfma_f32_16x16x32_bf16 v[64:67], v[176:179], v[236:239], v[64:67]
	s_setprio 0
	s_barrier
; #define PG8_STAGE(bufoff, gbase, voff) do { _Pragma("unroll") for (int _i = 0; _i < 2; ++_i) \
;         __builtin_amdgcn_global_load_lds((const unsigned*)((const char*)(gbase) + (voff)[_i]), (LAS unsigned*)(lds + (bufoff) + ldsw + _i * 8192), 16, 0, 0); } while (0)
; #define PG8_LDA(dst, b, h) do { _Pragma("unroll") for (int m = 0; m < 4; ++m) _Pragma("unroll") for (int k = 0; k < 2; ++k) dst[m][k] = *(const LAS bf16x8*)(lds + PG8_SA(b, h) + aoff + m * 2048 + k * 1024); } while (0)
; #define PG8_MMA(ai, bj, At, Bt) do { __builtin_amdgcn_s_setprio(1); _Pragma("unroll") for (int m = 0; m < 4; ++m) _Pragma("unroll") for (int n = 0; n < 2; ++n) _Pragma("unroll") for (int k = 0; k < 2; ++k) \
;         acc[ai][bj][m][n] = __builtin_amdgcn_mfma_f32_16x16x32_bf16(Bt[n][k], At[m][k], acc[ai][bj][m][n], 0, 0, 0); __builtin_amdgcn_s_setprio(0); } while (0)
; #define PG8_WAIT_V(n) asm volatile("s_waitcnt vmcnt(" #n ")" ::: "memory")
; #define PG8_WAIT_L(n) asm volatile("s_waitcnt lgkmcnt(" #n ")" ::: "memory")
; #define PG8_BAR __builtin_amdgcn_s_barrier()
; #define PG8_SCHED __builtin_amdgcn_sched_barrier(0)
; template <class Epi, bool ALIGN_EPI, bool SP2, bool ROWHALF = false>
; DI void gemm_phase(LAS unsigned char* lds, const Gemm g, const StaticOrder& S, const Epi& E) {
;     ...
;             if constexpr (!ROWHALF) { PG8_LDA(At, 1, 1); } PG8_STAGE(PG8_SB(1, 0), b3, voffB); PG8_STAGE(PG8_SB(1, 1), b3 + hstepB, voffB); PG8_STAGE(PG8_SA(1, 0), a3 + hA0, voffA);
;             PG8_WAIT_V(8); PG8_WAIT_L(0); PG8_BAR; if constexpr (!ROWHALF) { PG8_MMA(1, 0, At, B0); PG8_MMA(1, 1, At, B1); } PG8_BAR; PG8_SCHED;
	ds_read_b128 v[180:183], v147 offset:49152
	ds_read_b128 v[184:187], v147 offset:50176
	ds_read_b128 v[216:219], v147 offset:51200
	ds_read_b128 v[220:223], v147 offset:52224
	ds_read_b128 v[224:227], v147 offset:53248
	ds_read_b128 v[228:231], v147 offset:54272
	ds_read_b128 v[232:235], v147 offset:55296
	ds_read_b128 v[236:239], v147 offset:56320
	global_load_lds_dwordx4 v[160:161], off
	s_add_i32 m0, s36, 0x2000
	s_add_u32 s36, s76, 0x80080
	v_lshl_add_u64 v[160:161], v[240:241], 0, s[38:39]
	s_addc_u32 s37, s77, 0
	s_add_i32 s54, s55, s8
	global_load_lds_dwordx4 v[160:161], off
	v_lshl_add_u64 v[160:161], s[36:37], 0, v[96:97]
	s_mov_b32 m0, s54
	s_nop 0
	global_load_lds_dwordx4 v[160:161], off
	v_lshl_add_u64 v[160:161], s[36:37], 0, v[130:131]
	s_add_i32 m0, s54, 0x2000
	s_nop 0
	global_load_lds_dwordx4 v[160:161], off
	v_lshl_add_u64 v[160:161], v[242:243], 0, s[38:39]
	s_mov_b32 m0, s31
	s_nop 0
	global_load_lds_dwordx4 v[160:161], off
	v_lshl_add_u64 v[160:161], v[244:245], 0, s[38:39]
	s_mov_b32 m0, s46
	s_nop 0
	global_load_lds_dwordx4 v[160:161], off
	s_waitcnt vmcnt(8)
	s_waitcnt lgkmcnt(0)
	s_setprio 1
	v_mfma_f32_16x16x32_bf16 v[60:63], v[140:143], v[180:183], v[60:63]
	v_mfma_f32_16x16x32_bf16 v[52:55], v[152:155], v[180:183], v[52:55]
	v_mfma_f32_16x16x32_bf16 v[44:47], v[140:143], v[216:219], v[44:47]
	v_mfma_f32_16x16x32_bf16 v[36:39], v[152:155], v[216:219], v[36:39]
	s_barrier
	v_mfma_f32_16x16x32_bf16 v[28:31], v[140:143], v[224:227], v[28:31]
	v_mfma_f32_16x16x32_bf16 v[20:23], v[152:155], v[224:227], v[20:23]
	v_mfma_f32_16x16x32_bf16 v[12:15], v[140:143], v[232:235], v[12:15]
	v_mfma_f32_16x16x32_bf16 v[4:7], v[152:155], v[232:235], v[4:7]
	v_mfma_f32_16x16x32_bf16 v[60:63], v[148:151], v[184:187], v[60:63]
	v_mfma_f32_16x16x32_bf16 v[52:55], v[156:159], v[184:187], v[52:55]
	v_mfma_f32_16x16x32_bf16 v[44:47], v[148:151], v[220:223], v[44:47]
	v_mfma_f32_16x16x32_bf16 v[36:39], v[156:159], v[220:223], v[36:39]
	v_mfma_f32_16x16x32_bf16 v[28:31], v[148:151], v[228:231], v[28:31]
	v_mfma_f32_16x16x32_bf16 v[20:23], v[156:159], v[228:231], v[20:23]
	v_mfma_f32_16x16x32_bf16 v[12:15], v[148:151], v[236:239], v[12:15]
	v_mfma_f32_16x16x32_bf16 v[4:7], v[156:159], v[236:239], v[4:7]
	s_setprio 0
	s_setprio 1
	v_mfma_f32_16x16x32_bf16 v[56:59], v[164:167], v[180:183], v[56:59]
	s_add_i32 s53, s53, 2
	v_mfma_f32_16x16x32_bf16 v[48:51], v[172:175], v[180:183], v[48:51]
	s_add_u32 s74, s74, 0x100
	s_addc_u32 s75, s75, 0
	v_mfma_f32_16x16x32_bf16 v[40:43], v[164:167], v[216:219], v[40:43]
	s_add_u32 s47, s47, 0x100
	s_addc_u32 s51, s51, 0
	v_mfma_f32_16x16x32_bf16 v[32:35], v[172:175], v[216:219], v[32:35]
	s_add_u32 s36, s74, 0xfff80080
	s_addc_u32 s37, s75, -1
	v_mfma_f32_16x16x32_bf16 v[24:27], v[164:167], v[224:227], v[24:27]
	s_add_i32 s54, 0, 0x10000
	v_mfma_f32_16x16x32_bf16 v[16:19], v[172:175], v[224:227], v[16:19]
	s_cmp_eq_u32 s53, 28
	s_cselect_b32 s79, s20, s37
	v_mfma_f32_16x16x32_bf16 v[8:11], v[164:167], v[232:235], v[8:11]
	s_cselect_b32 s78, s21, s36
	s_cselect_b32 s77, s29, s51
	v_mfma_f32_16x16x32_bf16 v[0:3], v[172:175], v[232:235], v[0:3]
	s_cselect_b32 s76, s43, s47
	s_add_i32 s55, 0, 0x14000
	v_mfma_f32_16x16x32_bf16 v[56:59], v[168:171], v[184:187], v[56:59]
	v_mfma_f32_16x16x32_bf16 v[48:51], v[176:179], v[184:187], v[48:51]
	v_mfma_f32_16x16x32_bf16 v[40:43], v[168:171], v[220:223], v[40:43]
	v_mfma_f32_16x16x32_bf16 v[32:35], v[176:179], v[220:223], v[32:35]
	v_mfma_f32_16x16x32_bf16 v[24:27], v[168:171], v[228:231], v[24:27]
	v_mfma_f32_16x16x32_bf16 v[16:19], v[176:179], v[228:231], v[16:19]
	v_mfma_f32_16x16x32_bf16 v[8:11], v[168:171], v[236:239], v[8:11]
	v_mfma_f32_16x16x32_bf16 v[0:3], v[176:179], v[236:239], v[0:3]
	s_setprio 0
	s_cmp_gt_u32 s53, 29
	s_barrier
	s_cbranch_scc0 .Lk240_body
	s_and_b64 vcc, exec, s[24:25]
	s_cbranch_vccz .LBB0_243
	s_barrier
